# op-record prefetch: next op's 128B record loaded into spare VGPRs before the grid barrier instead of after it (from v29)
# speedup vs baseline: 1.0027x; 1.0027x over previous
; __device__ __forceinline__ void xcd_barrier_complete(unsigned* bar, unsigned x, unsigned& nloc, unsigned& nx) {
;     const unsigned G = gridDim.x * gridDim.y * gridDim.z;
;     unsigned sum, cnt, mine, sp = 0u;
;     for (;;) {
;         sum = 0u; cnt = 0u; mine = 0u;
; #pragma unroll
;         for (unsigned j = 0; j < 16; ++j) { const unsigned c = xb_ld(&bar[XB_XCNT(j)]); sum += c; cnt += (c > 0u) ? 1u : 0u; mine = (j == x) ? c : mine; }
;         if (sum == G) break;
;         __builtin_amdgcn_s_sleep(1);
;         if ((++sp & 255u) == 0u) { if (xb_ld(&bar[XB_TMO])) break; if (sp > XB_SPIN_CAP) { atomicAdd(&bar[XB_TMO], 1u); break; } }
;     }
;     nloc = mine > 0u ? mine : 1u; nx = cnt > 0u ? cnt : 1u;
; }
; __device__ __forceinline__ void xcd_barrier(const XcdBarrier& b) {
;     asm volatile("s_waitcnt vmcnt(0)" ::: "memory");
;     __syncthreads();
;     if (threadIdx.x == 0) {
;         unsigned* bar = b.bar;
;         __builtin_amdgcn_s_waitcnt(0);
;         unsigned nloc = b.st[0], nx = b.st[1];
;         if (nloc == 0u) { xcd_barrier_complete(bar, b.x, nloc, nx); b.st[0] = nloc; b.st[1] = nx; }
;         const unsigned old = xb_add(&bar[XB_XSUB(b.x)], 1u);
;         const unsigned gen = old / nloc;
;         if (old + 1u == (gen + 1u) * nloc) {
;             __builtin_amdgcn_fence(__ATOMIC_RELEASE, "agent");
;             asm volatile("s_waitcnt vmcnt(0)" ::: "memory");
;             const unsigned og = xb_add(&bar[XB_TOP], 1u);
;             const unsigned tg = og / nx;
;             if (og + 1u == (tg + 1u) * nx) xb_add(&bar[XB_TOPGEN], 1u);
;             else XB_SPIN(xb_ld(&bar[XB_TOPGEN]) == tg, bar);
;             __builtin_amdgcn_fence(__ATOMIC_ACQUIRE, "agent");
;             xb_add(&bar[XB_XGEN(b.x)], 1u);
;             asm volatile("s_waitcnt vmcnt(0)" ::: "memory");
;         } else {
;             XB_SPIN(xb_ld(&bar[XB_XGEN(b.x)]) == gen, bar);
;             __builtin_amdgcn_fence(__ATOMIC_ACQUIRE, "agent");
;             asm volatile("s_waitcnt vmcnt(0)" ::: "memory");
;         }
;     }
;     __syncthreads();
; }
; __global__ void __launch_bounds__(NTHREADS, 2) fwd_megakernel(Args a) {
;     ...
;         Op d;
;         {
;             const unsigned* p = (const unsigned*)(c.ws + WS_OPTAB) + (size_t)__builtin_amdgcn_readfirstlane(op) * 32;
;             unsigned w[32];
; #pragma unroll
.LBB0_392:
	s_load_dwordx2 s[4:5], s[0:1], 0x120
	v_mov_b32_e32 v97, 0
	v_mov_b32_e32 v180, 0x3a27c5ac
	v_mov_b32_e32 v181, 0x260
	v_mov_b32_e32 v182, 0x358637bd
	s_waitcnt lgkmcnt(0)
	s_mov_b64 s[6:7], s[4:5]
	s_load_dword s4, s[0:1], 0x128
	v_mov_b32_e32 v183, 1
	v_mov_b32_e32 v184, 0x1400
	v_mov_b32_e32 v185, 0xff800000
	v_mov_b32_e32 v186, 0x8300000
	s_waitcnt lgkmcnt(0)
	s_mul_i32 s4, s7, s4
	s_mul_i32 s23, s4, s6
	s_add_u32 s4, s2, 0x10200
	s_addc_u32 s5, s3, 0
	v_writelane_b32 v233, s4, 55
	v_mov_b32_e32 v187, 0x3b000000
	v_mov_b32_e32 v188, 0x3e000000
	v_writelane_b32 v233, s5, 56
	s_add_u32 s4, s2, 0x10400
	s_addc_u32 s5, s3, 0
	v_writelane_b32 v233, s4, 44
	s_mov_b32 s53, 0
	s_mov_b64 s[56:57], 0x80
	v_writelane_b32 v233, s5, 45
	s_add_u32 s4, s2, 0x10500
	s_addc_u32 s5, s3, 0
	v_writelane_b32 v233, s4, 10
	s_nop 1
	v_writelane_b32 v233, s5, 11
	s_add_u32 s4, s2, 0x10600
	s_addc_u32 s5, s3, 0
	v_writelane_b32 v233, s4, 8
	s_nop 1
	v_writelane_b32 v233, s5, 9
	s_add_u32 s4, s2, 0x10700
	s_addc_u32 s5, s3, 0
	v_writelane_b32 v233, s4, 12
	s_nop 1
	v_writelane_b32 v233, s5, 13
	s_add_u32 s4, s2, 0x10800
	s_addc_u32 s5, s3, 0
	v_writelane_b32 v233, s4, 24
	s_nop 1
	v_writelane_b32 v233, s5, 25
	s_add_u32 s4, s2, 0x10900
	s_addc_u32 s5, s3, 0
	v_writelane_b32 v233, s4, 34
	s_nop 1
	v_writelane_b32 v233, s5, 35
	s_add_u32 s4, s2, 0x10a00
	s_addc_u32 s5, s3, 0
	v_writelane_b32 v233, s4, 14
	s_nop 1
	v_writelane_b32 v233, s5, 15
	s_add_u32 s4, s2, 0x10b00
	s_addc_u32 s5, s3, 0
	v_writelane_b32 v233, s4, 16
	s_nop 1
	v_writelane_b32 v233, s5, 17
	s_add_u32 s4, s2, 0x10c00
	s_addc_u32 s5, s3, 0
	v_writelane_b32 v233, s4, 18
	s_nop 1
	v_writelane_b32 v233, s5, 19
	s_add_u32 s4, s2, 0x10d00
	s_addc_u32 s5, s3, 0
	v_writelane_b32 v233, s4, 20
	s_nop 1
	v_writelane_b32 v233, s5, 21
	s_add_u32 s4, s2, 0x10e00
	s_addc_u32 s5, s3, 0
	v_writelane_b32 v233, s4, 22
	s_nop 1
	v_writelane_b32 v233, s5, 23
	s_add_u32 s4, s2, 0x10f00
	s_addc_u32 s5, s3, 0
	v_writelane_b32 v233, s4, 26
	s_nop 1
	v_writelane_b32 v233, s5, 27
	s_add_u32 s4, s2, 0x11000
	s_addc_u32 s5, s3, 0
	v_writelane_b32 v233, s4, 28
	s_nop 1
	v_writelane_b32 v233, s5, 29
	s_add_u32 s4, s2, 0x11100
	s_addc_u32 s5, s3, 0
	v_writelane_b32 v233, s4, 30
	s_nop 1
	v_writelane_b32 v233, s5, 31
	s_add_u32 s4, s2, 0x11200
	s_addc_u32 s5, s3, 0
	v_writelane_b32 v233, s4, 32
	s_nop 1
	v_writelane_b32 v233, s5, 33
	s_add_u32 s4, s2, 0x11300
	s_addc_u32 s5, s3, 0
	v_writelane_b32 v233, s4, 36
	s_cmp_eq_u32 s33, 15
	s_nop 0
	v_writelane_b32 v233, s5, 37
	s_cselect_b64 s[4:5], -1, 0
	v_writelane_b32 v233, s4, 57
	s_cmp_eq_u32 s33, 14
	s_nop 0
	v_writelane_b32 v233, s5, 58
	s_cselect_b64 s[4:5], -1, 0
	v_writelane_b32 v233, s4, 59
	s_cmp_eq_u32 s33, 13
	s_nop 0
	v_writelane_b32 v233, s5, 60
	s_cselect_b64 s[4:5], -1, 0
	v_writelane_b32 v233, s4, 61
	s_cmp_eq_u32 s33, 12
	s_nop 0
	v_writelane_b32 v233, s5, 62
	s_cselect_b64 s[4:5], -1, 0
	v_writelane_b32 v233, s4, 63
	s_cmp_eq_u32 s33, 11
	s_nop 0
	v_writelane_b32 v232, s5, 0
	s_cselect_b64 s[4:5], -1, 0
	v_writelane_b32 v232, s4, 1
	s_cmp_eq_u32 s33, 10
	s_nop 0
	v_writelane_b32 v232, s5, 2
	s_cselect_b64 s[4:5], -1, 0
	v_writelane_b32 v232, s4, 3
	s_cmp_eq_u32 s33, 9
	s_nop 0
	v_writelane_b32 v232, s5, 4
	s_cselect_b64 s[4:5], -1, 0
	v_writelane_b32 v232, s4, 5
	s_cmp_eq_u32 s33, 8
	s_nop 0
	v_writelane_b32 v232, s5, 6
	s_cselect_b64 s[4:5], -1, 0
	v_writelane_b32 v232, s4, 7
	s_cmp_eq_u32 s33, 7
	s_nop 0
	v_writelane_b32 v232, s5, 8
	s_cselect_b64 s[4:5], -1, 0
	v_writelane_b32 v232, s4, 9
	s_cmp_eq_u32 s33, 6
	s_nop 0
	v_writelane_b32 v232, s5, 10
	s_cselect_b64 s[4:5], -1, 0
	v_writelane_b32 v232, s4, 11
	s_cmp_eq_u32 s33, 5
	s_nop 0
	v_writelane_b32 v232, s5, 12
	s_cselect_b64 s[4:5], -1, 0
	v_writelane_b32 v232, s4, 13
	s_cmp_eq_u32 s33, 4
	s_nop 0
	v_writelane_b32 v232, s5, 14
	s_cselect_b64 s[4:5], -1, 0
	v_writelane_b32 v232, s4, 15
	s_cmp_eq_u32 s33, 3
	s_nop 0
	v_writelane_b32 v232, s5, 16
	s_cselect_b64 s[4:5], -1, 0
	v_writelane_b32 v232, s4, 17
	s_cmp_eq_u32 s33, 2
	s_nop 0
	v_writelane_b32 v232, s5, 18
	s_cselect_b64 s[4:5], -1, 0
	v_writelane_b32 v232, s4, 19
	s_cmp_eq_u32 s33, 1
	s_nop 0
	v_writelane_b32 v232, s5, 20
	s_cselect_b64 s[4:5], -1, 0
	v_writelane_b32 v232, s4, 21
	s_cmp_eq_u32 s33, 0
	s_nop 0
	v_writelane_b32 v232, s5, 22
	s_cselect_b64 s[4:5], -1, 0
	v_writelane_b32 v232, s4, 23
	s_nop 1
	v_writelane_b32 v232, s5, 24
	s_lshl_b32 s4, s33, 8
	s_add_u32 s4, s24, s4
	s_addc_u32 s5, s25, 0
	s_add_u32 s6, s4, 0x1400
	s_addc_u32 s7, s5, 0
	v_writelane_b32 v232, s6, 25
	s_add_u32 s4, s4, 0x2400
	s_addc_u32 s5, s5, 0
	v_writelane_b32 v232, s7, 26
	v_writelane_b32 v232, s4, 27
	s_mov_b32 s33, 0x800000
	s_nop 0
	v_writelane_b32 v232, s5, 28
	s_add_u32 s4, s2, 0x13400
	s_addc_u32 s5, s3, 0
	v_writelane_b32 v232, s4, 29
	s_add_u32 s2, s2, 0x13500
	s_addc_u32 s3, s3, 0
	v_writelane_b32 v232, s5, 30
	v_writelane_b32 v232, s2, 31
	s_load_dwordx4 s[4:7], s[0:1], 0x108
	s_nop 0
	v_writelane_b32 v232, s3, 32
	s_add_i32 s2, 0, 0x1a000
	v_writelane_b32 v232, s2, 33
	s_add_i32 s2, 0, 0x19000
	v_writelane_b32 v232, s2, 34
	s_add_i32 s2, 0, 0xc000
	v_writelane_b32 v232, s2, 35
	s_add_i32 s2, 0, 0xa100
	v_writelane_b32 v232, s2, 36
	s_add_i32 s2, 0, 0x500
	v_writelane_b32 v232, s2, 37
	s_add_i32 s2, 0, 0x23fc0
	v_writelane_b32 v232, s2, 38
	s_add_i32 s2, 0, 0x23fc4
	v_writelane_b32 v232, s2, 39
	s_waitcnt lgkmcnt(0)
	v_writelane_b32 v232, s4, 40
	s_nop 1
	v_writelane_b32 v232, s5, 41
	v_writelane_b32 v232, s6, 42
	v_writelane_b32 v232, s7, 43
	v_writelane_b32 v232, s23, 44
	s_lshl_b32 s2, s42, 7
	s_add_u32 s4, s6, s2
	s_addc_u32 s5, s7, 0
	s_add_u32 s4, s4, 0x1000
	s_addc_u32 s5, s5, 0
	v_mov_b64_e32 v[228:229], s[4:5]
	global_load_dwordx4 v[200:203], v[228:229], off
	global_load_dwordx4 v[204:207], v[228:229], off offset:16
	global_load_dwordx4 v[208:211], v[228:229], off offset:32
	global_load_dword v219, v[228:229], off offset:48
	global_load_dwordx3 v[216:218], v[228:229], off offset:56
	global_load_dwordx4 v[212:215], v[228:229], off offset:72
	global_load_dwordx3 v[220:222], v[228:229], off offset:88
	global_load_dwordx3 v[224:226], v[228:229], off offset:104
	s_branch .LBB0_396

; template <class Sched>
; DI void gemm_phase(LAS unsigned char* lds, const Gemm g, const Sched& S, const Epi& E, const int wid) {
;     const int lane = lane_opaque(), tid = wid * 64 + lane, wr = wid >> 2, wc = wid & 3, fr = lane & 15, fq = lane >> 4;
;     const int K = g.K, nt = K / BK;
;     const bool PERM = S.perm(E);
;     unsigned voffA[2], voffB[2];
; #pragma unroll
;     for (int i = 0; i < 2; ++i) { int R, C; stage_rc(tid * 16 + i * 8192, R, C); const int Rb = PERM ? ((R & ~31) + perm32(R & 31)) : R;
;         voffA[i] = (unsigned)(R * g.lda + C) * 2u; voffB[i] = (unsigned)(Rb * g.ldb + C) * 2u; }
;     const size_t kstep = (size_t)(BK * 2);
; __global__ void __launch_bounds__(NTHREADS, 2) fwd_megakernel(Args a) {
;     ...
;             unsigned long long po = (unsigned long long)a.out, pw = (unsigned long long)a.ws; int b_ = blockIdx.x, g_ = gridDim.x, w_ = w0;
;             asm volatile("" : "+s"(po), "+s"(pw), "+s"(b_), "+s"(g_), "+s"(w_));
;             const unsigned long long pol = (unsigned)__builtin_amdgcn_readfirstlane((int)(unsigned)po), poh = (unsigned)__builtin_amdgcn_readfirstlane((int)(unsigned)(po >> 32));
;             const unsigned long long pwl = (unsigned)__builtin_amdgcn_readfirstlane((int)(unsigned)pw), pwh = (unsigned)__builtin_amdgcn_readfirstlane((int)(unsigned)(pw >> 32));
;             c.out = (float*)(pol | (poh << 32)); c.ws = (unsigned char*)(pwl | (pwh << 32));
;             c.bid = __builtin_amdgcn_readfirstlane(b_); c.G = __builtin_amdgcn_readfirstlane(g_); c.w0 = __builtin_amdgcn_readfirstlane(w_);
;         }
;         Op d;
;         {
;             const unsigned* p = (const unsigned*)(c.ws + WS_OPTAB) + (size_t)__builtin_amdgcn_readfirstlane(op) * 32;
;             unsigned w[32];
; #pragma unroll
;             for (int i = 0; i < 32; ++i) w[i] = (unsigned)__builtin_amdgcn_readfirstlane((int)p[i]);
;             __builtin_memcpy(&d, w, 128);
;         }
;     ...
;         const bool idem = (d.kind != K_GEMM) || (d.emode == pg8::EM_BF16 || d.emode == pg8::EM_DECAY) || (d.emode == pg8::EM_RESID && ((REP_MASK >> 9) & 1));
;         const int reps = (((REP_MASK >> d.kind) & 1) && idem && d.kind != K_FINAL && d.mg == 0) ? 2 : 1;
;         for (int rep = 0; rep < reps; ++rep) {
;         if (rep) __syncthreads();
;     ...
;         if (d.kind == K_GEMM && d.mg > 0) {
;             pg8::Gemm g{d.A, d.Bt, d.lda, d.ldb, d.N, d.K};
.LBB0_396:
	v_readlane_b32 s0, v232, 40
	v_readlane_b32 s1, v232, 41
	v_readlane_b32 s2, v232, 42
	v_readlane_b32 s3, v232, 43
	s_mov_b64 s[58:59], s[2:3]
	s_mov_b64 s[2:3], s[0:1]
	v_readlane_b32 s0, v233, 0
	v_readlane_b32 s60, v233, 1
	s_mov_b32 s78, s0
	v_readlane_b32 s12, v233, 52
	v_readlane_b32 s61, v233, 2
	v_writelane_b32 v232, s2, 45
	s_nop 1
	v_writelane_b32 v232, s3, 46
	s_add_u32 s2, s58, 0x1000
	s_addc_u32 s3, s59, 0
	s_ashr_i32 s43, s42, 31
	s_lshl_b64 s[0:1], s[42:43], 7
	s_add_u32 s0, s2, s0
	s_addc_u32 s1, s3, s1
	s_waitcnt vmcnt(0)
	v_mov_b32_e32 v0, v200
	v_mov_b32_e32 v1, v201
	v_mov_b32_e32 v2, v202
	v_mov_b32_e32 v3, v203
	v_mov_b32_e32 v4, v204
	v_mov_b32_e32 v5, v205
	v_mov_b32_e32 v6, v206
	v_mov_b32_e32 v7, v207
	v_mov_b32_e32 v8, v208
	v_mov_b32_e32 v9, v209
	v_mov_b32_e32 v10, v210
	v_mov_b32_e32 v11, v211
	v_mov_b32_e32 v12, v212
	v_mov_b32_e32 v13, v213
	v_mov_b32_e32 v14, v214
	v_mov_b32_e32 v15, v215
	v_mov_b32_e32 v16, v216
	v_mov_b32_e32 v17, v217
	v_mov_b32_e32 v18, v218
	v_mov_b32_e32 v19, v219
	v_mov_b32_e32 v20, v220
	v_mov_b32_e32 v21, v221
	v_mov_b32_e32 v22, v222
	v_mov_b32_e32 v24, v224
	v_mov_b32_e32 v25, v225
	v_mov_b32_e32 v26, v226
	v_writelane_b32 v232, s2, 47
	v_writelane_b32 v232, s3, 48
	s_waitcnt vmcnt(0) lgkmcnt(0)
	v_readfirstlane_b32 s0, v1
	s_nop 1
	v_writelane_b32 v232, s0, 49
	v_readfirstlane_b32 s0, v2
	v_readfirstlane_b32 s20, v0
	s_cmp_lg_u32 s20, 1
	v_writelane_b32 v232, s0, 50
	v_readfirstlane_b32 s0, v3
	v_readfirstlane_b32 s1, v13
	v_readfirstlane_b32 s16, v6
	v_writelane_b32 v232, s0, 51
	v_readfirstlane_b32 s0, v5
	v_readfirstlane_b32 s54, v26
	v_readfirstlane_b32 s8, v9
	v_writelane_b32 v233, s0, 46
	v_readfirstlane_b32 s0, v8
	s_mov_b32 s14, s16
	v_readfirstlane_b32 s18, v7
	v_writelane_b32 v232, s0, 52
	v_readfirstlane_b32 s0, v10
	v_readfirstlane_b32 s55, v4
	v_readfirstlane_b32 s76, v16
	v_writelane_b32 v232, s0, 53
	v_readfirstlane_b32 s0, v11
	v_readfirstlane_b32 s77, v17
	v_readfirstlane_b32 s75, v18
	v_writelane_b32 v233, s0, 5
	v_readfirstlane_b32 s0, v19
	v_readfirstlane_b32 s2, v14
	v_readfirstlane_b32 s3, v15
	v_writelane_b32 v233, s0, 40
	v_readfirstlane_b32 s0, v12
	v_readfirstlane_b32 s81, v22
	v_readfirstlane_b32 s72, v24
	v_writelane_b32 v233, s0, 3
	v_readfirstlane_b32 s73, v25
	s_nop 0
	v_writelane_b32 v233, s1, 4
	v_readfirstlane_b32 s0, v20
	s_nop 1
	v_writelane_b32 v233, s0, 38
	v_readfirstlane_b32 s0, v21
	s_nop 1
	v_writelane_b32 v232, s0, 54
	s_cselect_b64 s[0:1], -1, 0
	s_cmp_eq_u32 s20, 1
	s_cselect_b64 s[4:5], -1, 0
	s_cmp_gt_i32 s54, 0
	s_cselect_b64 s[6:7], -1, 0
	s_ashr_i32 s10, s8, 31
	v_writelane_b32 v232, s14, 55
	s_lshl_b32 s11, s12, 5
	s_lshr_b32 s10, s10, 26
	v_writelane_b32 v232, s15, 56
	s_mov_b32 s14, s18
	s_ashr_i32 s9, s12, 2
	s_ashr_i32 s17, s16, 31
	s_ashr_i32 s19, s18, 31
	v_writelane_b32 v232, s14, 57
	s_and_b32 s79, s11, 0x60
	s_and_b64 s[6:7], s[4:5], s[6:7]
	s_add_i32 s4, s8, s10
	s_lshl_b32 s80, s12, 6
	s_ashr_i32 s61, s60, 31
	s_lshl_b32 s62, s12, 10
	s_lshl_b64 s[64:65], s[16:17], 8
	s_lshl_b64 s[66:67], s[18:19], 8
	s_lshl_b64 s[68:69], s[16:17], 9
	v_writelane_b32 v232, s15, 58
	s_lshl_b64 s[70:71], s[18:19], 9
	s_lshl_b32 s13, s9, 13
	s_lshr_b32 s5, s79, 3
	s_ashr_i32 s63, s4, 6
	v_writelane_b32 v232, s13, 59
	s_cmp_eq_u32 s9, 1
	v_writelane_b32 v232, s5, 60
	s_cselect_b64 s[4:5], -1, 0
	v_writelane_b32 v232, s4, 61
	s_cmp_gt_i32 s8, 63
	s_nop 0
	v_writelane_b32 v232, s5, 62
	s_cselect_b64 s[4:5], -1, 0
	s_add_i32 s74, s63, -2
	v_writelane_b32 v232, s4, 63
	s_cmp_lt_u32 s12, 4
	s_nop 0
	v_writelane_b32 v231, s5, 0
	s_cselect_b64 s[4:5], -1, 0
	v_writelane_b32 v231, s4, 1
	s_nop 1
	v_writelane_b32 v231, s5, 2
	s_lshl_b32 s4, s12, 4
	s_andn2_b32 s4, s4, 63
	s_cmpk_eq_i32 s60, 0x100
	v_writelane_b32 v231, s4, 3
	s_cselect_b64 s[4:5], -1, 0
	v_writelane_b32 v231, s4, 4
	s_nop 1
	v_writelane_b32 v231, s5, 5
	s_lshl_b32 s4, s12, 14
	v_writelane_b32 v231, s12, 6
	s_add_i32 s4, s4, 0
	v_writelane_b32 v231, s4, 7
	s_add_u32 s4, s58, 0x6300000
	s_addc_u32 s5, s59, 0
	v_writelane_b32 v231, s4, 8
	s_nop 1
	v_writelane_b32 v231, s5, 9
	s_add_u32 s4, s58, 0x7b00000
	s_addc_u32 s5, s59, 0
	v_writelane_b32 v231, s4, 10
	s_nop 1
	v_writelane_b32 v231, s5, 11
	v_writelane_b32 v231, s6, 12
	s_andn2_b64 vcc, exec, s[6:7]
	s_mov_b64 s[4:5], -1
	v_writelane_b32 v231, s7, 13
	s_cbranch_vccnz .LBB0_397
	s_getpc_b64 s[98:99]

; __global__ void __launch_bounds__(NTHREADS, 2) fwd_megakernel(Args a) {
;     ...
;             const unsigned* p = (const unsigned*)(c.ws + WS_OPTAB) + (size_t)__builtin_amdgcn_readfirstlane(op) * 32;
;             unsigned w[32];
; #pragma unroll
;             for (int i = 0; i < 32; ++i) w[i] = (unsigned)__builtin_amdgcn_readfirstlane((int)p[i]);
;             __builtin_memcpy(&d, w, 128);
;     ...
;         if (d.kind == K_GEMM && d.mg > 0) op += (d.mg & 255) + ((d.mg >> 8) & 255) - 1;
;         if (d.sync && op + 1 < a.op_hi) { for (int r = 0; r < SYNC_REP; ++r) xcd_barrier(xbar); } else __syncthreads();
.LBB0_943:
	s_add_i32 s0, s16, s17
	s_add_i32 s2, s0, -1
	v_readlane_b32 s0, v231, 12
	v_readlane_b32 s1, v231, 13
	s_and_b64 s[0:1], s[0:1], exec
	s_cselect_b32 s0, s2, 0
	s_add_i32 s0, s0, s42
	v_readlane_b32 s1, v232, 49
	s_cmp_lg_u32 s1, 0
	s_cselect_b64 s[2:3], -1, 0
	s_add_i32 s42, s0, 1
	v_readlane_b32 s0, v233, 53
	v_readlane_b32 s1, v233, 54
	s_mov_b32 s5, s1
	s_cmp_ge_i32 s42, s1
	s_cselect_b64 s[0:1], -1, 0
	s_cmp_lt_i32 s42, s5
	s_cselect_b64 s[4:5], -1, 0
	s_and_b64 s[2:3], s[2:3], s[4:5]
	s_andn2_b64 vcc, exec, s[2:3]
	s_mov_b64 s[2:3], -1
	v_readlane_b32 s4, v232, 42
	v_readlane_b32 s5, v232, 43
	s_lshl_b32 s23, s42, 7
	s_add_u32 s4, s4, s23
	s_addc_u32 s5, s5, 0
	s_add_u32 s4, s4, 0x1000
	s_addc_u32 s5, s5, 0
	v_mov_b64_e32 v[228:229], s[4:5]
	global_load_dwordx4 v[200:203], v[228:229], off
	global_load_dwordx4 v[204:207], v[228:229], off offset:16
	global_load_dwordx4 v[208:211], v[228:229], off offset:32
	global_load_dword v219, v[228:229], off offset:48
	global_load_dwordx3 v[216:218], v[228:229], off offset:56
	global_load_dwordx4 v[212:215], v[228:229], off offset:72
	global_load_dwordx3 v[220:222], v[228:229], off offset:88
	global_load_dwordx3 v[224:226], v[228:229], off offset:104
	v_readlane_b32 s23, v232, 44
	s_cbranch_vccz .LBB0_945
	s_waitcnt vmcnt(0) lgkmcnt(0)
	s_barrier
	s_mov_b64 s[2:3], 0
